# baseline (speedup 1.0000x reference)
; __device__ __forceinline__ int ltid() { int t = threadIdx.x; asm volatile("" : "+v"(t)); return t; }
; __device__ __forceinline__ float wave_sum(float v) {
; #pragma unroll
;   for (int o = 32; o > 0; o >>= 1) v += __shfl_xor(v, o, 64);
;   return v;
; __device__ void nvec_items(const Ctx& p, const int hd) {
;   char* ws = p.ws;
;   const u16* KTh = (const u16*)(ws + OFF_KTH);
;   const float* gA = (const float*)(ws + OFF_GAA);
;   float* nv = (float*)(ws + OFF_NVEC);
;   const int tid = ltid(), w = tid >> 6, lane = tid & 63;
;   for (int item = blockIdx.x; item < 2 * 256; item += gridDim.x) {
;     const int b = item >> 8, d = (item & 255) * 8 + w;
;     const int bh = b * 4 + hd;
;     float st = 0.f;
.LBB0_588:
	v_readlane_b32 s0, v253, 61
	v_readlane_b32 s1, v253, 62
	v_mov_b32_e32 v0, v139
	s_andn2_b64 vcc, exec, s[0:1]
	s_waitcnt lgkmcnt(0)
	s_barrier
	s_cbranch_vccnz .LBB0_597
	s_waitcnt vmcnt(0)
	v_add_u32_e32 v3, 64, v196
	v_xor_b32_e32 v4, 32, v195
	v_cmp_lt_i32_e32 vcc, v4, v3
	s_add_u32 s10, s66, 0x8400000
	s_addc_u32 s11, s67, 0
	v_cndmask_b32_e32 v4, v195, v4, vcc
	v_lshlrev_b32_e32 v7, 2, v4
	v_xor_b32_e32 v4, 16, v195
	v_cmp_lt_i32_e32 vcc, v4, v3
	s_add_u32 s12, s66, 0x436c0000
	s_addc_u32 s13, s67, 0
	v_cndmask_b32_e32 v4, v195, v4, vcc
	v_lshlrev_b32_e32 v8, 2, v4
	v_xor_b32_e32 v4, 8, v195
	v_cmp_lt_i32_e32 vcc, v4, v3
	v_and_b32_e32 v2, 63, v0
	s_add_u32 s0, s66, 0x43750000
	v_cndmask_b32_e32 v4, v195, v4, vcc
	v_lshlrev_b32_e32 v9, 2, v4
	v_xor_b32_e32 v4, 4, v195
	v_cmp_lt_i32_e32 vcc, v4, v3
	v_ashrrev_i32_e32 v6, 6, v0
	v_lshlrev_b32_e32 v0, 3, v2
	v_cndmask_b32_e32 v4, v195, v4, vcc
	v_lshlrev_b32_e32 v10, 2, v4
	v_xor_b32_e32 v4, 2, v195
	v_cmp_lt_i32_e32 vcc, v4, v3
	s_addc_u32 s1, s67, 0
	v_cmp_eq_u32_e64 s[4:5], 0, v2
	v_cndmask_b32_e32 v4, v195, v4, vcc
	v_lshlrev_b32_e32 v11, 2, v4
	v_xor_b32_e32 v4, 1, v195
	v_cmp_lt_i32_e32 vcc, v4, v3
	v_lshlrev_b32_e32 v0, 1, v0
	v_readlane_b32 s14, v253, 17
	v_cndmask_b32_e32 v3, v195, v4, vcc
	v_lshlrev_b32_e32 v12, 2, v3
	s_sub_i32 s15, s63, 0x80
	s_cmp_lt_i32 s15, 0
	s_cbranch_scc1 .LBB0_597
	s_and_b32 s14, s15, 7
	s_cmp_lt_u32 s14, 2
	s_cbranch_scc1 .LBB0_597
	s_lshr_b32 s15, s15, 3
	s_mul_i32 s15, s15, 6
	s_add_i32 s15, s15, s14
	s_add_i32 s15, s15, -2
	s_lshl_b32 s14, s15, 3
	s_branch .LBB0_591
.LBB0_590:
	s_or_b64 exec, exec, s[8:9]
	s_addk_i32 s15, 0x60
	s_addk_i32 s14, 0x300
	s_cmpk_gt_i32 s15, 0x1ff
	s_cbranch_scc1 .LBB0_597
